# diff-attn loop re-emitted: MFMA-interleaved PV/QK, running-max bookkeeping in first PV group gaps, rescale applied to O after PV, scalar-base K/V prefetch addressing
# speedup vs baseline: 1.0283x; 1.0283x over previous
.LBB0_322:
	v_add_f32_e32 v16, 0, v16
	v_add_f32_e32 v32, 0, v32
	v_add_f32_e32 v16, v17, v16
	v_add_f32_e32 v17, v33, v32
	v_add_f32_e32 v16, v18, v16
	v_add_f32_e32 v17, v34, v17
	v_add_f32_e32 v16, v19, v16
	v_add_f32_e32 v17, v35, v17
	v_add_f32_e32 v16, v20, v16
	v_add_f32_e32 v17, v36, v17
	v_add_f32_e32 v16, v21, v16
	v_add_f32_e32 v17, v37, v17
	v_add_f32_e32 v16, v22, v16
	v_add_f32_e32 v17, v38, v17
	v_add_f32_e32 v16, v23, v16
	v_add_f32_e32 v17, v39, v17
	v_add_f32_e32 v16, v24, v16
	v_add_f32_e32 v17, v40, v17
	v_add_f32_e32 v16, v25, v16
	v_add_f32_e32 v17, v41, v17
	v_add_f32_e32 v16, v26, v16
	v_add_f32_e32 v17, v42, v17
	v_add_f32_e32 v16, v27, v16
	v_add_f32_e32 v17, v43, v17
	v_add_f32_e32 v16, v28, v16
	v_add_f32_e32 v17, v44, v17
	v_add_f32_e32 v16, v29, v16
	v_add_f32_e32 v17, v45, v17
	v_add_f32_e32 v16, v30, v16
	v_add_f32_e32 v17, v46, v17
	v_add_f32_e32 v16, v31, v16
	v_add_f32_e32 v17, v47, v17
	v_add_f32_e32 v16, v16, v17
	v_add_f32_e32 v167, v0, v16
	v_lshrrev_b32_e32 v16, 2, v159
	v_and_or_b32 v16, v16, 3, v157
	s_andn2_b64 vcc, exec, s[2:3]
	v_mul_u32_u24_e32 v168, 0x140, v16
	s_cbranch_vccnz .LBB0_339
	s_add_i32 s2, 0, 0x18000
	v_lshl_add_u32 v190, v129, 2, s2
	v_mul_u32_u24_e32 v16, 0x1800, v130
	v_and_b32_e32 v18, 15, v159
	v_lshl_or_b32 v150, v18, 4, v16
	v_add_u32_e32 v151, 0x30000, v150
	s_mul_i32 s60, s12, 0x3000000
	s_add_u32 s60, s92, s60
	s_addc_u32 s61, s93, 0
	s_add_u32 s60, s60, s90
	s_addc_u32 s61, s61, s91
	s_add_u32 s60, s60, 0xda42000
	s_addc_u32 s61, s61, 0
	v_readlane_b32 s2, v254, 58
	v_lshlrev_b32_e32 v17, 1, v159
	v_and_b32_e32 v18, 3, v159
	v_add_u32_e32 v16, s2, v168
	v_and_b32_e32 v17, 32, v17
	v_lshlrev_b32_e32 v18, 3, v18
	v_add3_u32 v191, v16, v17, v18
	v_mul_u32_u24_e32 v16, 0x1800, v128
	v_and_b32_e32 v18, 7, v159
	v_lshl_or_b32 v16, v18, 4, v16
	v_add_u32_e32 v152, 0x5f800, v16
	v_mov_b64_e32 v[30:31], v[14:15]
	v_mov_b64_e32 v[46:47], v[14:15]
	v_mov_b64_e32 v[62:63], v[14:15]
	v_mov_b64_e32 v[130:131], v[106:107]
	v_mov_b64_e32 v[134:135], v[98:99]
	s_sub_i32 s22, s23, 63
	s_mov_b32 s23, 2
	s_add_i32 s24, s15, 2
	s_mov_b32 s34, 1
	s_or_b32 s14, s15, 1
	s_not_b32 s25, s15
	s_add_i32 s26, s19, s13
	s_mov_b32 s27, 0
	v_mov_b64_e32 v[28:29], v[12:13]
	v_mov_b64_e32 v[26:27], v[10:11]
	v_mov_b64_e32 v[24:25], v[8:9]
	v_mov_b64_e32 v[22:23], v[6:7]
	v_mov_b64_e32 v[20:21], v[4:5]
	v_mov_b64_e32 v[18:19], v[2:3]
	v_mov_b64_e32 v[16:17], v[0:1]
	v_mov_b64_e32 v[44:45], v[12:13]
	v_mov_b64_e32 v[42:43], v[10:11]
	v_mov_b64_e32 v[40:41], v[8:9]
	v_mov_b64_e32 v[38:39], v[6:7]
	v_mov_b64_e32 v[36:37], v[4:5]
	v_mov_b64_e32 v[34:35], v[2:3]
	v_mov_b64_e32 v[32:33], v[0:1]
	v_mov_b64_e32 v[60:61], v[12:13]
	v_mov_b64_e32 v[58:59], v[10:11]
	v_mov_b64_e32 v[56:57], v[8:9]
	v_mov_b64_e32 v[54:55], v[6:7]
	v_mov_b64_e32 v[52:53], v[4:5]
	v_mov_b64_e32 v[50:51], v[2:3]
	v_mov_b64_e32 v[48:49], v[0:1]
	v_mov_b64_e32 v[128:129], v[104:105]
	v_mov_b64_e32 v[132:133], v[96:97]
.LBB0_325:
	s_mul_hi_u32 s4, s27, 0xaaaaaaab
	s_lshr_b32 s4, s4, 1
	s_mul_i32 s4, s4, 0xf000
	v_subrev_u32_e32 v178, s4, v191
	ds_read_b64_tr_b16 v[128:129], v178 offset:0
	ds_read_b64_tr_b16 v[130:131], v178 offset:2560
	ds_read_b64_tr_b16 v[132:133], v178 offset:64
	ds_read_b64_tr_b16 v[134:135], v178 offset:2624
	ds_read_b64_tr_b16 v[136:137], v178 offset:128
	ds_read_b64_tr_b16 v[138:139], v178 offset:2688
	ds_read_b64_tr_b16 v[140:141], v178 offset:192
	ds_read_b64_tr_b16 v[142:143], v178 offset:2752
	s_cmp_lt_i32 s34, s15
	s_cselect_b64 s[2:3], -1, 0
	s_waitcnt vmcnt(0)
	s_cbranch_scc0 .Lda_t_skip_stk
	s_bitcmp1_b32 s34, 0
	s_cselect_b32 s12, 0x4800, 0
	v_add_u32_e32 v214, s12, v163
	ds_write_b128 v214, v[96:99]
	ds_write_b128 v214, v[104:107] offset:9216
.Lda_t_skip_stk:
	s_add_i32 s35, s34, 1
	s_cmp_lt_i32 s35, s24
	s_cbranch_scc0 .Lda_t_skip_stv
	s_mul_hi_u32 s12, s23, 0xaaaaaaab
	s_lshr_b32 s12, s12, 1
	s_mul_i32 s12, s12, 0xffff1000
	s_add_i32 s12, s12, 0x13000
	v_add_u32_e32 v250, s12, v164
	ds_write_b128 v250, v[100:103]
	ds_write_b128 v250, v[108:111] offset:10240
.Lda_t_skip_stv:
	s_add_i32 s12, s34, 3
	s_cmp_ge_i32 s12, s24
	s_cbranch_scc1 .Lda_t_skip_ldk
	global_load_dwordx4 v[96:99], v152, s[60:61]
	global_load_dwordx4 v[104:107], v152, s[60:61] offset:128
.Lda_t_skip_ldk:
	s_andn2_b64 vcc, exec, s[2:3]
	s_cbranch_vccnz .LBB0_327
	global_load_dwordx4 v[100:103], v150, s[60:61]
	global_load_dwordx4 v[108:111], v151, s[60:61]
.LBB0_327:
	s_waitcnt lgkmcnt(6)
	v_mfma_f32_32x32x16_bf16 v[48:63], v[128:131], v[124:127], v[48:63]
	ds_read_b64_tr_b16 v[230:231], v178 offset:5120
	ds_read_b64_tr_b16 v[232:233], v178 offset:7680
	v_max3_f32 v148, v64, v65, v66
	v_max3_f32 v154, v80, v81, v82
	v_max3_f32 v148, v148, v67, v68
	v_max3_f32 v154, v154, v83, v84
	v_max3_f32 v148, v148, v69, v70
	s_waitcnt lgkmcnt(6)
	v_mfma_f32_32x32x16_bf16 v[32:47], v[132:135], v[124:127], v[32:47]
	ds_read_b64_tr_b16 v[234:235], v178 offset:5184
	ds_read_b64_tr_b16 v[236:237], v178 offset:7744
	v_max3_f32 v154, v154, v85, v86
	v_max3_f32 v148, v148, v71, v72
	v_max3_f32 v154, v154, v87, v88
	v_max3_f32 v148, v148, v73, v74
	v_max3_f32 v154, v154, v89, v90
	s_waitcnt lgkmcnt(6)
	v_mfma_f32_32x32x16_bf16 v[16:31], v[136:139], v[124:127], v[16:31]
	ds_read_b64_tr_b16 v[238:239], v178 offset:5248
	ds_read_b64_tr_b16 v[240:241], v178 offset:7808
	v_max3_f32 v148, v148, v75, v76
	v_max3_f32 v154, v154, v91, v92
	v_max_f32_e32 v155, v95, v95
	v_max_f32_e32 v170, v79, v79
	v_max3_f32 v148, v148, v77, v78
	s_waitcnt lgkmcnt(6)
	v_mfma_f32_32x32x16_bf16 v[0:15], v[140:143], v[124:127], v[0:15]
	ds_read_b64_tr_b16 v[242:243], v178 offset:5312
	ds_read_b64_tr_b16 v[244:245], v178 offset:7872
	v_max3_f32 v154, v154, v93, v94
	v_max_f32_e32 v155, v170, v155
	v_max3_f32 v154, v148, v154, v155
	v_mov_b32_e32 v155, v154
	s_cmpk_gt_i32 s26, 0x5e8
	s_cselect_b64 vcc, -1, 0
	v_permlane32_swap_b32_e32 v155, v154
	v_cndmask_b32_e32 v148, 0, v165, vcc
	v_max_f32_e32 v170, v154, v155
	v_pk_add_f32 v[154:155], v[148:149], v[170:171]
	s_nop 0
	v_cmp_gt_f32_e32 vcc, v154, v155
	s_mov_b32 s58, 0
	s_cbranch_vccz .LBB0_329
	v_max_f32_e32 v154, v154, v154
	v_max_f32_e32 v155, v149, v149
	v_max_f32_e32 v155, v155, v154
	v_sub_f32_e32 v149, v149, v155
	v_exp_f32_e32 v250, v149
	s_mov_b32 s58, 1
	v_mov_b32_e32 v149, v155
	v_mul_f32_e32 v167, v167, v250
.LBB0_329:
	v_sub_f32_e32 v179, v149, v148
	s_waitcnt lgkmcnt(6)
	v_mfma_f32_32x32x16_bf16 v[48:63], v[230:233], v[120:123], v[48:63]
	ds_read_b64_tr_b16 v[128:129], v178 offset:10240
	ds_read_b64_tr_b16 v[130:131], v178 offset:12800
	v_sub_f32_e32 v148, v64, v179
	v_exp_f32_e32 v148, v148
	v_sub_f32_e32 v192, v80, v179
	v_exp_f32_e32 v192, v192
	v_sub_f32_e32 v154, v65, v179
	v_exp_f32_e32 v154, v154
	s_waitcnt lgkmcnt(6)
	v_mfma_f32_32x32x16_bf16 v[32:47], v[234:237], v[120:123], v[32:47]
	ds_read_b64_tr_b16 v[132:133], v178 offset:10304
	ds_read_b64_tr_b16 v[134:135], v178 offset:12864
	v_sub_f32_e32 v193, v81, v179
	v_exp_f32_e32 v193, v193
	v_sub_f32_e32 v155, v66, v179
	v_exp_f32_e32 v155, v155
	v_sub_f32_e32 v194, v82, v179
	v_exp_f32_e32 v194, v194
	s_waitcnt lgkmcnt(6)
	v_mfma_f32_32x32x16_bf16 v[16:31], v[238:241], v[120:123], v[16:31]
	ds_read_b64_tr_b16 v[136:137], v178 offset:10368
	ds_read_b64_tr_b16 v[138:139], v178 offset:12928
	v_sub_f32_e32 v170, v67, v179
	v_exp_f32_e32 v170, v170
	v_sub_f32_e32 v195, v83, v179
	v_exp_f32_e32 v195, v195
	v_sub_f32_e32 v196, v68, v179
	v_exp_f32_e32 v196, v196
	s_waitcnt lgkmcnt(6)
	v_mfma_f32_32x32x16_bf16 v[0:15], v[242:245], v[120:123], v[0:15]
	ds_read_b64_tr_b16 v[140:141], v178 offset:10432
	ds_read_b64_tr_b16 v[142:143], v178 offset:12992
	v_sub_f32_e32 v200, v84, v179
	v_exp_f32_e32 v200, v200
	v_sub_f32_e32 v197, v69, v179
	v_exp_f32_e32 v197, v197
	v_sub_f32_e32 v201, v85, v179
	v_exp_f32_e32 v201, v201
	s_waitcnt lgkmcnt(6)
	v_mfma_f32_32x32x16_bf16 v[48:63], v[128:131], v[116:119], v[48:63]
	ds_read_b64_tr_b16 v[230:231], v178 offset:15360
	ds_read_b64_tr_b16 v[232:233], v178 offset:17920
	v_sub_f32_e32 v198, v70, v179
	v_exp_f32_e32 v198, v198
	v_sub_f32_e32 v202, v86, v179
	v_exp_f32_e32 v202, v202
	v_sub_f32_e32 v199, v71, v179
	v_exp_f32_e32 v199, v199
	s_waitcnt lgkmcnt(6)
	v_mfma_f32_32x32x16_bf16 v[32:47], v[132:135], v[116:119], v[32:47]
	ds_read_b64_tr_b16 v[234:235], v178 offset:15424
	ds_read_b64_tr_b16 v[236:237], v178 offset:17984
	v_sub_f32_e32 v203, v87, v179
	v_exp_f32_e32 v203, v203
	v_sub_f32_e32 v204, v72, v179
	v_exp_f32_e32 v204, v204
	v_sub_f32_e32 v208, v88, v179
	v_exp_f32_e32 v208, v208
	s_waitcnt lgkmcnt(6)
	v_mfma_f32_32x32x16_bf16 v[16:31], v[136:139], v[116:119], v[16:31]
	ds_read_b64_tr_b16 v[238:239], v178 offset:15488
	ds_read_b64_tr_b16 v[240:241], v178 offset:18048
	v_sub_f32_e32 v205, v73, v179
	v_exp_f32_e32 v205, v205
	v_sub_f32_e32 v209, v89, v179
	v_exp_f32_e32 v209, v209
	v_sub_f32_e32 v206, v74, v179
	v_exp_f32_e32 v206, v206
	s_waitcnt lgkmcnt(6)
	v_mfma_f32_32x32x16_bf16 v[0:15], v[140:143], v[116:119], v[0:15]
	ds_read_b64_tr_b16 v[242:243], v178 offset:15552
	ds_read_b64_tr_b16 v[244:245], v178 offset:18112
	v_sub_f32_e32 v220, v90, v179
	v_exp_f32_e32 v220, v220
	v_sub_f32_e32 v207, v75, v179
	v_exp_f32_e32 v207, v207
	v_sub_f32_e32 v221, v91, v179
	v_exp_f32_e32 v221, v221
	s_add_i32 s35, s34, 1
	s_cmp_lt_i32 s35, s24
	s_cselect_b64 s[4:5], -1, 0
	s_and_b64 s[12:13], s[4:5], exec
	s_cselect_b32 s36, s35, s14
	s_lshl_b32 s54, s36, 6
	s_bitcmp1_b32 s36, 0
	s_cselect_b32 s13, 0x4800, 0
	v_add_u32_e32 v214, s13, v166
	s_sub_i32 s12, s22, s54
	s_waitcnt lgkmcnt(6)
	v_mfma_f32_32x32x16_bf16 v[48:63], v[230:233], v[112:115], v[48:63]
	ds_read_b128 v[246:249], v162
	ds_read_b128 v[128:131], v214
	ds_read_b128 v[132:135], v214 offset:4608
	v_sub_f32_e32 v222, v76, v179
	v_exp_f32_e32 v222, v222
	v_sub_f32_e32 v226, v92, v179
	v_exp_f32_e32 v226, v226
	v_sub_f32_e32 v223, v77, v179
	v_exp_f32_e32 v223, v223
	s_waitcnt lgkmcnt(7)
	v_mfma_f32_32x32x16_bf16 v[32:47], v[234:237], v[112:115], v[32:47]
	ds_read_b128 v[136:139], v214 offset:32
	ds_read_b128 v[140:143], v214 offset:4640
	v_sub_f32_e32 v227, v93, v179
	v_exp_f32_e32 v227, v227
	v_sub_f32_e32 v224, v78, v179
	v_exp_f32_e32 v224, v224
	v_sub_f32_e32 v228, v94, v179
	v_exp_f32_e32 v228, v228
	s_waitcnt lgkmcnt(7)
	v_mfma_f32_32x32x16_bf16 v[16:31], v[238:241], v[112:115], v[16:31]
	v_sub_f32_e32 v225, v79, v179
	v_exp_f32_e32 v225, v225
	v_sub_f32_e32 v229, v95, v179
	v_exp_f32_e32 v229, v229
	s_waitcnt lgkmcnt(5)
	v_mfma_f32_32x32x16_bf16 v[0:15], v[242:245], v[112:115], v[0:15]
	s_cmp_lg_u32 s58, 0
	s_cbranch_scc0 .Lda_noscale
	s_nop 15
	v_pk_mul_f32 v[62:63], v[62:63], v[250:251] op_sel_hi:[1,0]
	v_pk_mul_f32 v[60:61], v[60:61], v[250:251] op_sel_hi:[1,0]
	v_pk_mul_f32 v[58:59], v[58:59], v[250:251] op_sel_hi:[1,0]
	v_pk_mul_f32 v[56:57], v[56:57], v[250:251] op_sel_hi:[1,0]
	v_pk_mul_f32 v[54:55], v[54:55], v[250:251] op_sel_hi:[1,0]
	v_pk_mul_f32 v[52:53], v[52:53], v[250:251] op_sel_hi:[1,0]
	v_pk_mul_f32 v[50:51], v[50:51], v[250:251] op_sel_hi:[1,0]
	v_pk_mul_f32 v[48:49], v[48:49], v[250:251] op_sel_hi:[1,0]
	v_pk_mul_f32 v[46:47], v[46:47], v[250:251] op_sel_hi:[1,0]
	v_pk_mul_f32 v[44:45], v[44:45], v[250:251] op_sel_hi:[1,0]
	v_pk_mul_f32 v[42:43], v[42:43], v[250:251] op_sel_hi:[1,0]
	v_pk_mul_f32 v[40:41], v[40:41], v[250:251] op_sel_hi:[1,0]
	v_pk_mul_f32 v[38:39], v[38:39], v[250:251] op_sel_hi:[1,0]
	v_pk_mul_f32 v[36:37], v[36:37], v[250:251] op_sel_hi:[1,0]
	v_pk_mul_f32 v[34:35], v[34:35], v[250:251] op_sel_hi:[1,0]
	v_pk_mul_f32 v[32:33], v[32:33], v[250:251] op_sel_hi:[1,0]
	v_pk_mul_f32 v[30:31], v[30:31], v[250:251] op_sel_hi:[1,0]
	v_pk_mul_f32 v[28:29], v[28:29], v[250:251] op_sel_hi:[1,0]
	v_pk_mul_f32 v[26:27], v[26:27], v[250:251] op_sel_hi:[1,0]
	v_pk_mul_f32 v[24:25], v[24:25], v[250:251] op_sel_hi:[1,0]
	v_pk_mul_f32 v[22:23], v[22:23], v[250:251] op_sel_hi:[1,0]
	v_pk_mul_f32 v[20:21], v[20:21], v[250:251] op_sel_hi:[1,0]
	v_pk_mul_f32 v[18:19], v[18:19], v[250:251] op_sel_hi:[1,0]
	v_pk_mul_f32 v[16:17], v[16:17], v[250:251] op_sel_hi:[1,0]
	v_pk_mul_f32 v[14:15], v[14:15], v[250:251] op_sel_hi:[1,0]
	v_pk_mul_f32 v[12:13], v[12:13], v[250:251] op_sel_hi:[1,0]
	v_pk_mul_f32 v[10:11], v[10:11], v[250:251] op_sel_hi:[1,0]
	v_pk_mul_f32 v[8:9], v[8:9], v[250:251] op_sel_hi:[1,0]
	v_pk_mul_f32 v[6:7], v[6:7], v[250:251] op_sel_hi:[1,0]
	v_pk_mul_f32 v[4:5], v[4:5], v[250:251] op_sel_hi:[1,0]
	v_pk_mul_f32 v[2:3], v[2:3], v[250:251] op_sel_hi:[1,0]
	v_pk_mul_f32 v[0:1], v[0:1], v[250:251] op_sel_hi:[1,0]
.Lda_noscale:
	s_cmpk_lt_i32 s12, 0x5e9
	s_cbranch_scc0 .Lda_ld_qk
	s_sub_i32 s13, 0, s54
	v_lshl_add_u32 v215, s13, 2, v190
	ds_read2_b32 v[64:65], v215 offset0:128 offset1:127
	ds_read2_b32 v[66:67], v215 offset0:126 offset1:125
	ds_read2_b32 v[68:69], v215 offset0:120 offset1:119
	ds_read2_b32 v[70:71], v215 offset0:118 offset1:117
	ds_read2_b32 v[72:73], v215 offset0:112 offset1:111
	ds_read2_b32 v[74:75], v215 offset0:110 offset1:109
	ds_read2_b32 v[76:77], v215 offset0:104 offset1:103
	ds_read2_b32 v[78:79], v215 offset0:102 offset1:101
	ds_read2_b32 v[80:81], v215 offset0:96 offset1:95
	ds_read2_b32 v[82:83], v215 offset0:94 offset1:93
	ds_read2_b32 v[84:85], v215 offset0:88 offset1:87
	ds_read2_b32 v[86:87], v215 offset0:86 offset1:85
	ds_read2_b32 v[88:89], v215 offset0:80 offset1:79
	ds_read2_b32 v[90:91], v215 offset0:78 offset1:77
	ds_read2_b32 v[92:93], v215 offset0:72 offset1:71
	ds_read2_b32 v[94:95], v215 offset0:70 offset1:69
.Lda_ld_qk:
	ds_read_b128 v[230:233], v162 offset:1024
	ds_read_b128 v[234:237], v162 offset:2048
	ds_read_b128 v[238:241], v214 offset:64
	ds_read_b128 v[242:245], v214 offset:4672
	ds_read_b128 v[178:181], v162 offset:3072
	v_cvt_pk_bf16_f32 v124, v148, v154
	v_add_f32_e32 v250, v193, v192
	v_add_f32_e32 v251, v154, v148
	v_cvt_pk_bf16_f32 v125, v155, v170
	v_add_f32_e32 v250, v194, v250
	v_add_f32_e32 v251, v155, v251
	v_cvt_pk_bf16_f32 v126, v196, v197
	v_add_f32_e32 v250, v195, v250
	v_add_f32_e32 v251, v170, v251
	v_cvt_pk_bf16_f32 v127, v198, v199
	s_cmpk_lt_i32 s12, 0x5e9
	s_cbranch_scc0 .Lda_mm_far
	s_waitcnt lgkmcnt(5)
	v_mfma_f32_32x32x16_bf16 v[64:79], v[128:131], v[246:249], v[64:79]
	v_add_f32_e32 v250, v200, v250
	v_add_f32_e32 v251, v196, v251
	v_cvt_pk_bf16_f32 v116, v192, v193
	v_add_f32_e32 v250, v201, v250
	v_add_f32_e32 v251, v197, v251
	v_mfma_f32_32x32x16_bf16 v[80:95], v[132:135], v[246:249], v[80:95]
	s_branch .Lda_mm_rest
.Lda_mm_far:
	s_waitcnt lgkmcnt(8)
	v_mfma_f32_32x32x16_bf16 v[64:79], v[128:131], v[246:249], 0
	v_add_f32_e32 v250, v200, v250
	v_add_f32_e32 v251, v196, v251
	v_cvt_pk_bf16_f32 v116, v192, v193
	v_add_f32_e32 v250, v201, v250
	v_add_f32_e32 v251, v197, v251
	s_waitcnt lgkmcnt(7)
	v_mfma_f32_32x32x16_bf16 v[80:95], v[132:135], v[246:249], 0
.Lda_mm_rest:
	ds_read_b128 v[128:131], v214 offset:96
	ds_read_b128 v[132:135], v214 offset:4704
	v_cvt_pk_bf16_f32 v117, v194, v195
	v_add_f32_e32 v250, v202, v250
	v_add_f32_e32 v251, v198, v251
	v_cvt_pk_bf16_f32 v118, v200, v201
	v_add_f32_e32 v250, v203, v250
	s_waitcnt lgkmcnt(6)
	v_mfma_f32_32x32x16_bf16 v[64:79], v[136:139], v[230:233], v[64:79]
	v_add_f32_e32 v251, v199, v251
	v_cvt_pk_bf16_f32 v119, v202, v203
	v_add_f32_e32 v250, v208, v250
	v_add_f32_e32 v251, v204, v251
	v_cvt_pk_bf16_f32 v120, v204, v205
	v_mfma_f32_32x32x16_bf16 v[80:95], v[140:143], v[230:233], v[80:95]
	v_add_f32_e32 v250, v209, v250
	v_add_f32_e32 v251, v205, v251
	v_cvt_pk_bf16_f32 v121, v206, v207
	v_add_f32_e32 v250, v220, v250
	v_add_f32_e32 v251, v206, v251
	s_waitcnt lgkmcnt(4)
	v_mfma_f32_32x32x16_bf16 v[64:79], v[238:241], v[234:237], v[64:79]
	v_cvt_pk_bf16_f32 v122, v222, v223
	v_add_f32_e32 v250, v221, v250
	v_add_f32_e32 v251, v207, v251
	v_cvt_pk_bf16_f32 v123, v224, v225
	v_add_f32_e32 v250, v226, v250
	s_waitcnt lgkmcnt(3)
	v_mfma_f32_32x32x16_bf16 v[80:95], v[242:245], v[234:237], v[80:95]
	v_add_f32_e32 v251, v222, v251
	v_cvt_pk_bf16_f32 v112, v208, v209
	v_add_f32_e32 v250, v227, v250
	v_add_f32_e32 v251, v223, v251
	v_cvt_pk_bf16_f32 v113, v220, v221
	s_waitcnt lgkmcnt(1)
	v_mfma_f32_32x32x16_bf16 v[64:79], v[128:131], v[178:181], v[64:79]
	v_add_f32_e32 v250, v228, v250
	v_add_f32_e32 v251, v224, v251
	v_cvt_pk_bf16_f32 v114, v226, v227
	v_add_f32_e32 v250, v229, v250
	v_add_f32_e32 v251, v225, v251
	s_waitcnt lgkmcnt(0)
	v_mfma_f32_32x32x16_bf16 v[80:95], v[132:135], v[178:181], v[80:95]
	v_cvt_pk_bf16_f32 v115, v228, v229
	v_add_f32_e32 v250, v250, v251
	v_add_f32_e32 v167, v167, v250
	s_add_i32 s23, s23, 1
	s_add_i32 s2, s25, s35
	s_add_i32 s27, s27, 1
	s_sub_i32 s26, s26, 64
	s_add_u32 s60, s60, s88
	s_addc_u32 s61, s61, s89
	v_add_u32_e32 v164, 0x5000, v164
	v_add_u32_e32 v191, 0x5000, v191
	s_cmp_eq_u32 s2, 1
	s_waitcnt lgkmcnt(0)
	s_barrier
	s_cbranch_scc1 .LBB0_340
	s_mov_b32 s34, s35
	s_branch .LBB0_325
